# delta consumer chain shortening (eg*S, beta*v, beta*eg off the dependent chain) on top of st3
# speedup vs baseline: 1.0177x; 1.0177x over previous
; __device__ __forceinline__ void delta_unit(const Params& P, LAS unsigned char* lds, int li, bool sample, int b, int h, int half, const int tid) {
;     ...
;             for (int tok = 0; tok < ntok; tok += 2) {
;                 DN_STEP(tok, kA0, kA1, qA0, qA1, vA, gA, kB0, kB1, qB0, qB1, vB, gB);
;                 DN_STEP(tok + 1, kB0, kB1, qB0, qB1, vB, gB, kA0, kA1, qA0, qA1, vA, gA);
;             }
.LBB0_650:
	s_waitcnt lgkmcnt(0)
	v_pk_mul_f32 v[118:119], v[38:39], v[66:67]
	v_pk_mul_f32 v[120:121], v[34:35], v[62:63]
	v_pk_fma_f32 v[118:119], v[36:37], v[68:69], v[118:119]
	v_pk_fma_f32 v[120:121], v[32:33], v[64:65], v[120:121]
	ds_read_b128 v[102:105], v99 offset:8192
	ds_read_b128 v[106:109], v99 offset:8208
	ds_read_b128 v[110:113], v99
	ds_read_b128 v[114:117], v99 offset:16
	ds_read_b32 v101, v98
	v_pk_add_f32 v[118:119], v[120:121], v[118:119]
	v_mov_b32_e32 v122, s1
	v_add_f32_e32 v118, v118, v119
	ds_read_b64 v[122:123], v122
	s_add_i32 s26, s25, 4
	v_pk_mul_f32 v[124:125], v[70:71], v[66:67] op_sel_hi:[0,1]
	v_pk_mul_f32 v[126:127], v[70:71], v[62:63] op_sel_hi:[0,1]
	v_add_f32_dpp v118, v118, v118 quad_perm:[1,0,3,2] row_mask:0xf bank_mask:0xf bound_ctrl:1
	s_min_u32 s26, s26, 31
	s_lshl_b32 s27, s26, 8
	v_pk_mul_f32 v[128:129], v[70:71], v[68:69] op_sel_hi:[0,1]
	v_pk_mul_f32 v[130:131], v[70:71], v[64:65] op_sel_hi:[0,1]
	v_add_f32_dpp v118, v118, v118 quad_perm:[2,3,0,1] row_mask:0xf bank_mask:0xf bound_ctrl:1
	s_lshl_b32 s26, s26, 3
	v_add_u32_e32 v119, s27, v96
	v_mul_f32_e32 v132, v71, v100
	v_mul_f32_e32 v133, v71, v70
	v_add_f32_dpp v118, v118, v118 row_half_mirror row_mask:0xf bank_mask:0xf bound_ctrl:1
	s_waitcnt lgkmcnt(0)
	v_fma_f32 v100, -v133, v118, v132
	v_pk_fma_f32 v[66:67], v[38:39], v[100:101], v[124:125] op_sel_hi:[1,0,1]
	v_pk_fma_f32 v[62:63], v[34:35], v[100:101], v[126:127] op_sel_hi:[1,0,1]
	v_pk_fma_f32 v[68:69], v[36:37], v[100:101], v[128:129] op_sel_hi:[1,0,1]
	v_pk_fma_f32 v[64:65], v[32:33], v[100:101], v[130:131] op_sel_hi:[1,0,1]
	v_pk_mul_f32 v[26:27], v[26:27], v[66:67]
	v_pk_mul_f32 v[30:31], v[30:31], v[62:63]
	v_pk_mul_f32 v[32:33], v[104:105], v[66:67]
	v_pk_mul_f32 v[34:35], v[108:109], v[62:63]
	v_pk_fma_f32 v[24:25], v[24:25], v[68:69], v[26:27]
	v_pk_fma_f32 v[26:27], v[28:29], v[64:65], v[30:31]
	v_pk_fma_f32 v[28:29], v[102:103], v[68:69], v[32:33]
	v_pk_fma_f32 v[30:31], v[106:107], v[64:65], v[34:35]
	v_pk_add_f32 v[24:25], v[24:25], v[26:27]
	v_pk_add_f32 v[26:27], v[28:29], v[30:31]
	v_add_f32_e32 v24, v24, v25
	v_add_f32_e32 v25, v26, v27
	s_add_i32 s26, s0, s26
	v_pk_mul_f32 v[124:125], v[122:123], v[66:67] op_sel_hi:[0,1]
	v_pk_mul_f32 v[126:127], v[122:123], v[62:63] op_sel_hi:[0,1]
	v_add_f32_dpp v24, v24, v24 quad_perm:[1,0,3,2] row_mask:0xf bank_mask:0xf bound_ctrl:1
	v_add_f32_dpp v25, v25, v25 quad_perm:[1,0,3,2] row_mask:0xf bank_mask:0xf bound_ctrl:1
	v_add_u32_e32 v120, s27, v97
	v_pk_mul_f32 v[128:129], v[122:123], v[68:69] op_sel_hi:[0,1]
	v_pk_mul_f32 v[130:131], v[122:123], v[64:65] op_sel_hi:[0,1]
	v_add_f32_dpp v24, v24, v24 quad_perm:[2,3,0,1] row_mask:0xf bank_mask:0xf bound_ctrl:1
	v_add_f32_dpp v25, v25, v25 quad_perm:[2,3,0,1] row_mask:0xf bank_mask:0xf bound_ctrl:1
	v_mov_b32_e32 v121, s26
	v_mul_f32_e32 v132, v123, v101
	v_mul_f32_e32 v133, v123, v122
	v_add_f32_dpp v24, v24, v24 row_half_mirror row_mask:0xf bank_mask:0xf bound_ctrl:1
	v_add_f32_dpp v25, v25, v25 row_half_mirror row_mask:0xf bank_mask:0xf bound_ctrl:1
	v_fma_f32 v118, -v133, v25, v132
	ds_write_b32 v98, v24 offset:7936
	ds_read_b128 v[36:39], v119 offset:8192
	ds_read_b128 v[32:35], v119 offset:8208
	ds_read_b128 v[24:27], v119
	ds_read_b128 v[28:31], v119 offset:16
	ds_read_b32 v100, v120 offset:16384
	ds_read_b64 v[70:71], v121 offset:32768
	v_pk_fma_f32 v[66:67], v[104:105], v[118:119], v[124:125] op_sel_hi:[1,0,1]
	v_pk_fma_f32 v[62:63], v[108:109], v[118:119], v[126:127] op_sel_hi:[1,0,1]
	v_pk_fma_f32 v[68:69], v[102:103], v[118:119], v[128:129] op_sel_hi:[1,0,1]
	v_pk_fma_f32 v[64:65], v[106:107], v[118:119], v[130:131] op_sel_hi:[1,0,1]
	v_pk_mul_f32 v[102:103], v[112:113], v[66:67]
	v_pk_mul_f32 v[104:105], v[116:117], v[62:63]
	v_pk_fma_f32 v[102:103], v[110:111], v[68:69], v[102:103]
	v_pk_fma_f32 v[104:105], v[114:115], v[64:65], v[104:105]
	s_add_i32 s25, s25, 2
	v_pk_add_f32 v[102:103], v[102:103], v[104:105]
	s_add_i32 s1, s1, 16
	v_add_f32_e32 v101, v102, v103
	v_add_u32_e32 v99, 0x200, v99
	s_cmp_lt_u32 s25, 30
	v_add_f32_dpp v101, v101, v101 quad_perm:[1,0,3,2] row_mask:0xf bank_mask:0xf bound_ctrl:1
	s_nop 1
	v_add_f32_dpp v101, v101, v101 quad_perm:[2,3,0,1] row_mask:0xf bank_mask:0xf bound_ctrl:1
	s_nop 1
	v_add_f32_dpp v101, v101, v101 row_half_mirror row_mask:0xf bank_mask:0xf bound_ctrl:1
	ds_write_b32 v98, v101 offset:8192
	v_add_u32_e32 v98, 0x200, v98
	s_cbranch_scc1 .LBB0_650
